# tile order remap also for proj (panel-major 16x4 per XCD) and merge (8x8 per XCD)
# speedup vs baseline: 1.0442x; 1.0059x over previous
; __device__ __forceinline__ int tidx() { int t = threadIdx.x; asm volatile("" : "+v"(t)); return t; }
; template <int NT>
; __device__ __forceinline__ void gemm_tile(f32x4 (&acc)[4][NT], const bf16_t* A, int lda, const bf16_t* B, int ldb, int K, bf16_t* sm) {
;     const int tid_ = tidx();
;     bf16_t* sA = sm; bf16_t* sB = sm + 128 * LDT;
;     const int tid = tid_, lane = tid & 63, wid = tid >> 6, wr = wid >> 1, wc = wid & 1;
;     const int fr = lane & 15, fq = lane >> 4;
;     const int lrow = tid >> 3, lkc = tid & 7;
;     const bf16_t* ga = A + (size_t)lrow * lda + lkc * 8;
;     const bf16_t* gb = B + (size_t)lrow * ldb + lkc * 8;
;     int sbrow[NT];
; #pragma unroll
;     for (int i = 0; i < NT; ++i) { const int g = lrow + 32 * i, W_ = 16 * NT, rem = g % W_; sbrow[i] = (g / W_) * W_ + (rem % NT) * 16 + rem / NT; }
; __device__ __forceinline__ void phase_proj(const bf16_t* xb, const bf16_t* W, bf16_t* P, bf16_t* sm) {
;     ...
;     for (int t = blockIdx.x; t < 136 * 37; t += gridDim.x) {
;         const int tm = t / 37, tn = t % 37;
;         f32x4 acc[4][4]; zero_acc<4>(acc);
;         gemm_tile<4>(acc, xb + (size_t)tm * 128 * 1024, 1024, W + (size_t)tn * 128 * 1024, 1024, 1024, sm);
.LBB0_464:
	v_mov_b32_e32 v38, v192
	s_lshr_b32 s2, s13, 9
	s_and_b32 s14, s13, 7
	s_bfe_u32 s15, s13, 0x60003
	s_cmp_eq_u32 s2, 9
	s_cselect_b32 s18, 53, 64
	s_mul_i32 s14, s14, s18
	s_lshl_b32 s2, s2, 9
	s_add_i32 s2, s2, s14
	s_add_i32 s2, s2, s15
	s_mul_i32 s14, s2, 0x7879
	s_lshr_b32 s14, s14, 24
	s_mul_i32 s15, s14, 0x220
	s_sub_i32 s15, s2, s15
	s_lshl_b32 s18, s14, 2
	s_and_b32 s19, s15, 3
	s_add_i32 s18, s18, s19
	s_lshr_b32 s14, s15, 2
	s_cmpk_lt_u32 s2, 0x1320
	s_cbranch_scc1 .Lproj_map_done
	s_sub_i32 s14, s2, 0x1320
	s_movk_i32 s18, 36
.Lproj_map_done:
	s_mov_b32 s15, 0
	v_ashrrev_i32_e32 v0, 31, v38
	s_waitcnt vmcnt(6)
	v_ashrrev_i32_e32 v30, 3, v38
	v_lshrrev_b32_e32 v0, 26, v0
	v_add_u32_e32 v0, v30, v0
	v_lshrrev_b32_e32 v1, 6, v0
	v_mul_i32_i24_e32 v1, 64, v1
	v_sub_u32_e32 v1, v30, v1
	v_lshrrev_b16_sdwa v2, v196, sext(v1) dst_sel:DWORD dst_unused:UNUSED_PAD src0_sel:DWORD src1_sel:BYTE_0
	v_and_b32_e32 v2, 3, v2
	v_add_u16_e32 v2, v1, v2
	v_ashrrev_i16_sdwa v3, v197, sext(v2) dst_sel:DWORD dst_unused:UNUSED_PAD src0_sel:DWORD src1_sel:BYTE_0
	v_and_b32_e32 v2, 0xfc, v2
	v_sub_u16_e32 v1, v1, v2
	v_and_b32_e32 v0, 0x7ffffc0, v0
	v_lshlrev_b32_sdwa v1, v198, sext(v1) dst_sel:DWORD dst_unused:UNUSED_PAD src0_sel:DWORD src1_sel:BYTE_0
	v_bfe_i32 v2, v3, 0, 16
	v_add3_u32 v39, v0, v2, v1
	v_add_u32_e32 v0, 32, v30
	v_ashrrev_i32_e32 v1, 31, v0
	v_lshrrev_b32_e32 v1, 26, v1
	v_add_u32_e32 v1, v0, v1
	v_lshrrev_b32_e32 v2, 6, v1
	v_mul_i32_i24_e32 v2, 64, v2
	v_sub_u32_e32 v0, v0, v2
	v_lshrrev_b16_sdwa v2, v196, sext(v0) dst_sel:DWORD dst_unused:UNUSED_PAD src0_sel:DWORD src1_sel:BYTE_0
	v_and_b32_e32 v2, 3, v2
	v_add_u16_e32 v2, v0, v2
	v_ashrrev_i16_sdwa v3, v197, sext(v2) dst_sel:DWORD dst_unused:UNUSED_PAD src0_sel:DWORD src1_sel:BYTE_0
	v_and_b32_e32 v2, 0xfc, v2
	v_sub_u16_e32 v0, v0, v2
	v_and_b32_e32 v1, 0x7ffffc0, v1
	v_lshlrev_b32_sdwa v0, v198, sext(v0) dst_sel:DWORD dst_unused:UNUSED_PAD src0_sel:DWORD src1_sel:BYTE_0
	v_bfe_i32 v2, v3, 0, 16
	v_add3_u32 v40, v1, v2, v0
	v_add_u32_e32 v0, 64, v30
	v_ashrrev_i32_e32 v1, 31, v0
	v_lshrrev_b32_e32 v1, 26, v1
	v_add_u32_e32 v1, v0, v1
	v_lshrrev_b32_e32 v2, 6, v1
	v_mul_i32_i24_e32 v2, 64, v2
	v_sub_u32_e32 v0, v0, v2
	v_lshrrev_b16_sdwa v2, v196, sext(v0) dst_sel:DWORD dst_unused:UNUSED_PAD src0_sel:DWORD src1_sel:BYTE_0
	v_and_b32_e32 v2, 3, v2
	v_add_u16_e32 v2, v0, v2
	v_ashrrev_i16_sdwa v3, v197, sext(v2) dst_sel:DWORD dst_unused:UNUSED_PAD src0_sel:DWORD src1_sel:BYTE_0
	v_and_b32_e32 v2, 0xfc, v2
	v_sub_u16_e32 v0, v0, v2
	v_and_b32_e32 v1, 0x7ffffc0, v1
	v_lshlrev_b32_sdwa v0, v198, sext(v0) dst_sel:DWORD dst_unused:UNUSED_PAD src0_sel:DWORD src1_sel:BYTE_0
	v_bfe_i32 v2, v3, 0, 16
	s_waitcnt lgkmcnt(0)
	v_add3_u32 v41, v1, v2, v0
	v_add_u32_e32 v0, 0x60, v30
	v_ashrrev_i32_e32 v1, 31, v0
	v_lshrrev_b32_e32 v1, 26, v1
	v_add_u32_e32 v1, v0, v1
	v_lshrrev_b32_e32 v2, 6, v1
	v_mul_i32_i24_e32 v2, 64, v2
	v_sub_u32_e32 v0, v0, v2
	v_lshrrev_b16_sdwa v2, v196, sext(v0) dst_sel:DWORD dst_unused:UNUSED_PAD src0_sel:DWORD src1_sel:BYTE_0
	s_lshl_b64 s[22:23], s[14:15], 18
	v_and_b32_e32 v2, 3, v2
	s_add_u32 s40, s80, s22
	v_add_u16_e32 v2, v0, v2
	s_addc_u32 s41, s81, s23
	s_ashr_i32 s19, s18, 31
	v_ashrrev_i16_sdwa v3, v197, sext(v2) dst_sel:DWORD dst_unused:UNUSED_PAD src0_sel:DWORD src1_sel:BYTE_0
	v_and_b32_e32 v2, 0xfc, v2
	s_lshl_b64 s[24:25], s[18:19], 18
	v_sub_u16_e32 v0, v0, v2
	s_add_u32 s42, s11, s24
	v_and_b32_e32 v1, 0x7ffffc0, v1
	v_lshlrev_b32_sdwa v0, v198, sext(v0) dst_sel:DWORD dst_unused:UNUSED_PAD src0_sel:DWORD src1_sel:BYTE_0
	v_bfe_i32 v2, v3, 0, 16
	v_ashrrev_i32_e32 v31, 31, v30
	s_addc_u32 s43, s12, s25
	v_add3_u32 v42, v1, v2, v0
	v_lshlrev_b64 v[32:33], 11, v[30:31]
	v_lshlrev_b32_e32 v2, 4, v38
	v_lshl_add_u64 v[0:1], s[42:43], 0, v[32:33]
	v_and_b32_e32 v12, 0x70, v2
	v_lshl_add_u64 v[8:9], v[0:1], 0, v[12:13]
	v_add_co_u32_e32 v0, vcc, s7, v8
	v_and_b32_e32 v31, 15, v38
	s_nop 0
	v_addc_co_u32_e32 v1, vcc, 0, v9, vcc
	v_add_co_u32_e32 v10, vcc, s37, v8
	v_mov_b32_e32 v250, v8
	v_mov_b32_e32 v251, v9
	s_nop 0
	v_addc_co_u32_e32 v11, vcc, 0, v9, vcc
	v_add_co_u32_e32 v14, vcc, s73, v8
	v_lshrrev_b32_e32 v44, 1, v38
	s_nop 0
	v_addc_co_u32_e32 v15, vcc, 0, v9, vcc
	s_nop 0
	v_lshl_add_u64 v[14:15], s[40:41], 0, v[32:33]
	v_lshl_add_u64 v[26:27], v[14:15], 0, v[12:13]
	v_add_co_u32_e32 v14, vcc, s7, v26
	v_and_or_b32 v31, v44, s3, v31
	s_nop 0
	v_addc_co_u32_e32 v15, vcc, 0, v27, vcc
	v_add_co_u32_e32 v28, vcc, s37, v26
	v_mov_b32_e32 v248, v26
	v_mov_b32_e32 v249, v27
	s_nop 0
	v_addc_co_u32_e32 v29, vcc, 0, v27, vcc
	v_add_co_u32_e32 v34, vcc, s73, v26
	v_mul_lo_u32 v44, v31, s89
	s_nop 0
	v_addc_co_u32_e32 v35, vcc, 0, v27, vcc
	s_nop 0
	v_mul_lo_u32 v45, v30, s89
	v_lshl_add_u64 v[30:31], s[22:23], 0, v[32:33]
	v_or_b32_e32 v30, v30, v12
	v_lshl_add_u64 v[98:99], s[58:59], 0, v[30:31]
	v_lshl_add_u64 v[30:31], s[24:25], 0, v[32:33]
	v_and_b32_e32 v43, 48, v38
	v_and_b32_e32 v38, 0x4f, v38
	v_or_b32_e32 v30, v30, v12
	v_mul_u32_u24_e32 v38, 0xa0, v38
	v_mul_lo_u32 v39, v39, s89
	v_mul_lo_u32 v40, v40, s89
	v_mul_lo_u32 v41, v41, s89
	v_mul_lo_u32 v42, v42, s89
; template <int NT>
; __device__ __forceinline__ void gemm_tile(f32x4 (&acc)[4][NT], const bf16_t* A, int lda, const bf16_t* B, int ldb, int K, bf16_t* sm) {
;     ...
;     const bf16_t* ga = A + (size_t)lrow * lda + lkc * 8;
;     const bf16_t* gb = B + (size_t)lrow * ldb + lkc * 8;
;     int sbrow[NT];
; #pragma unroll
;     for (int i = 0; i < NT; ++i) { const int g = lrow + 32 * i, W_ = 16 * NT, rem = g % W_; sbrow[i] = (g / W_) * W_ + (rem % NT) * 16 + rem / NT; }
;     u32x4 ra0[4], rb0[NT];
; #pragma unroll
;     for (int i = 0; i < 4; ++i) ra0[i] = *(const u32x4*)(ga + (size_t)(32 * i) * lda);
; #pragma unroll
;     for (int i = 0; i < NT; ++i) rb0[i] = *(const u32x4*)(gb + (size_t)(32 * i) * ldb);
;     const int nk = K >> 6;
;     for (int kt = 0; kt < nk; ++kt) {
;         lds_barrier();
; #pragma unroll
;         for (int i = 0; i < 4; ++i) *(u32x4*)(sA + (lrow + 32 * i) * LDT + lkc * 8) = ra0[i];
; #pragma unroll
;         for (int i = 0; i < NT; ++i) *(u32x4*)(sB + sbrow[i] * LDT + lkc * 8) = rb0[i];
;         lds_barrier();
;         if (kt + 1 < nk) {
;             ga += 64; gb += 64;
; #pragma unroll
;             for (int i = 0; i < 4; ++i) ra0[i] = *(const u32x4*)(ga + (size_t)(32 * i) * lda);
; #pragma unroll
;             for (int i = 0; i < NT; ++i) rb0[i] = *(const u32x4*)(gb + (size_t)(32 * i) * ldb);
;         }
	v_lshl_add_u64 v[100:101], s[58:59], 0, v[30:31]
	v_mov_b32_e32 v30, 0
	s_mov_b64 s[22:23], 0
	v_add_u32_e32 v105, v12, v45
	v_add_u32_e32 v106, v12, v39
	v_add_u32_e32 v107, v12, v40
	v_add_u32_e32 v108, v12, v41
	v_add_u32_e32 v109, v12, v42
	v_add_u32_e32 v104, v43, v44
	v_add_u32_e32 v12, v43, v38
	v_mov_b32_e32 v31, v30
	v_mov_b32_e32 v32, v30
	v_mov_b32_e32 v33, v30
	v_mov_b32_e32 v38, v30
	v_mov_b32_e32 v39, v30
	v_mov_b32_e32 v40, v30
	v_mov_b32_e32 v41, v30
	v_mov_b32_e32 v42, v30
	v_mov_b32_e32 v43, v30
	v_mov_b32_e32 v44, v30
	v_mov_b32_e32 v45, v30
	v_mov_b32_e32 v46, v30
	v_mov_b32_e32 v47, v30
	v_mov_b32_e32 v48, v30
	v_mov_b32_e32 v49, v30
	v_mov_b32_e32 v50, v30
	v_mov_b32_e32 v51, v30
	v_mov_b32_e32 v52, v30
	v_mov_b32_e32 v53, v30
	v_mov_b32_e32 v54, v30
	v_mov_b32_e32 v55, v30
	v_mov_b32_e32 v56, v30
	v_mov_b32_e32 v57, v30
	v_mov_b32_e32 v58, v30
	v_mov_b32_e32 v59, v30
	v_mov_b32_e32 v60, v30
	v_mov_b32_e32 v61, v30
	v_mov_b32_e32 v62, v30
	v_mov_b32_e32 v63, v30
	v_mov_b32_e32 v64, v30
	v_mov_b32_e32 v65, v30
	v_mov_b32_e32 v66, v30
	v_mov_b32_e32 v67, v30
	v_mov_b32_e32 v68, v30
	v_mov_b32_e32 v69, v30
	v_mov_b32_e32 v70, v30
	v_mov_b32_e32 v71, v30
	v_mov_b32_e32 v72, v30
	v_mov_b32_e32 v73, v30
	v_mov_b32_e32 v74, v30
	v_mov_b32_e32 v75, v30
	v_mov_b32_e32 v76, v30
	v_mov_b32_e32 v77, v30
	v_mov_b32_e32 v78, v30
	v_mov_b32_e32 v79, v30
	v_mov_b32_e32 v80, v30
	v_mov_b32_e32 v81, v30
	v_mov_b32_e32 v82, v30
	v_mov_b32_e32 v83, v30
	v_mov_b32_e32 v84, v30
	v_mov_b32_e32 v85, v30
	v_mov_b32_e32 v86, v30
	v_mov_b32_e32 v87, v30
	v_mov_b32_e32 v88, v30
	v_mov_b32_e32 v89, v30
	v_mov_b32_e32 v90, v30
	v_mov_b32_e32 v91, v30
	v_mov_b32_e32 v92, v30
	v_mov_b32_e32 v93, v30
	v_mov_b32_e32 v94, v30
	v_mov_b32_e32 v95, v30
	v_mov_b32_e32 v96, v30
	v_mov_b32_e32 v97, v30
	v_writelane_b32 v234, s90, 0
	v_writelane_b32 v234, s91, 1
	v_writelane_b32 v234, s92, 2
	v_writelane_b32 v234, s93, 3
	v_writelane_b32 v234, s94, 4
	v_writelane_b32 v234, s95, 5
	v_bfe_u32 v160, v192, 3, 3
	v_and_b32_e32 v161, 7, v192
	v_xor_b32_e32 v161, v160, v161
	v_lshlrev_b32_e32 v161, 4, v161
	v_lshrrev_b32_e32 v162, 6, v192
	v_lshl_add_u32 v163, v162, 5, v160
	v_mul_u32_u24_e32 v163, 0x800, v163
	v_add_u32_e32 v236, v163, v161
	v_add_u32_e32 v237, 0x3c00, v236
	v_add_u32_e32 v238, 0x3c00, v237
	v_add_u32_e32 v239, 0x3c00, v238
	v_lshrrev_b32_e32 v163, 7, v192
	v_bfe_u32 v162, v192, 6, 1
	v_lshlrev_b32_e32 v163, 6, v163
	v_lshl_add_u32 v163, v160, 2, v163
	v_lshl_add_u32 v163, v162, 1, v163
	v_mul_u32_u24_e32 v163, 0x800, v163
	v_add_u32_e32 v240, v163, v161
	v_add_u32_e32 v241, 0xfc00, v240
	v_subrev_u32_e32 v242, 0xfc00, v241
	v_add_u32_e32 v243, 0xfc00, v242
	v_and_b32_e32 v160, 15, v192
	v_bfe_u32 v161, v192, 4, 2
	v_and_b32_e32 v162, 7, v160
	v_xor_b32_e32 v161, v161, v162
	v_lshlrev_b32_e32 v161, 4, v161
	v_lshl_add_u32 v161, v160, 7, v161
	v_lshrrev_b32_e32 v162, 7, v192
	v_lshl_add_u32 v244, v162, 13, v161
	v_bfe_u32 v162, v192, 6, 1
	v_lshl_add_u32 v246, v162, 13, v161
	v_add_u32_e32 v246, 0x4000, v246
	v_xor_b32_e32 v245, 64, v244
	v_xor_b32_e32 v247, 64, v246
	v_lshrrev_b32_e32 v160, 6, v192
	s_nop 0
	v_readfirstlane_b32 s94, v160
	v_readfirstlane_b32 s90, v248
	v_readfirstlane_b32 s91, v249
	v_readfirstlane_b32 s92, v250
	v_readfirstlane_b32 s93, v251
	s_mul_i32 s95, s94, 0x4000
	s_sub_u32 s90, s90, s95
	s_subb_u32 s91, s91, 0
	s_mul_i32 s95, s94, 0x4000
	s_sub_u32 s92, s92, s95
	s_subb_u32 s93, s93, 0
	s_lshl_b32 s94, s94, 10
	s_waitcnt lgkmcnt(0)
	s_barrier
	s_lshl_b32 s95, s94, 2
	s_add_u32 m0, s95, 0x0
	s_nop 0
	global_load_lds_dwordx4 v236, s[90:91]
	global_load_lds_dwordx4 v237, s[90:91] offset:1024
	global_load_lds_dwordx4 v238, s[90:91] offset:2048
	global_load_lds_dwordx4 v239, s[90:91] offset:3072
	s_mul_i32 s95, s94, 4
	s_add_u32 m0, s95, 0x4000
	s_nop 0
	global_load_lds_dwordx4 v240, s[92:93]
	global_load_lds_dwordx4 v241, s[92:93] offset:1024
	global_load_lds_dwordx4 v242, s[92:93] offset:2048
	global_load_lds_dwordx4 v243, s[92:93] offset:3072
	s_add_u32 s90, s90, 0x80
	s_addc_u32 s91, s91, 0
	s_add_u32 s92, s92, 0x80
	s_addc_u32 s93, s93, 0
	s_waitcnt vmcnt(0)
	s_barrier
	s_lshl_b32 s95, s94, 2
	s_add_u32 m0, s95, 0x8000
	s_nop 0
	global_load_lds_dwordx4 v236, s[90:91]
	global_load_lds_dwordx4 v237, s[90:91] offset:1024
	global_load_lds_dwordx4 v238, s[90:91] offset:2048
	global_load_lds_dwordx4 v239, s[90:91] offset:3072
	s_mul_i32 s95, s94, 4
	s_add_u32 m0, s95, 0xc000
	s_nop 0
	global_load_lds_dwordx4 v240, s[92:93]
	global_load_lds_dwordx4 v241, s[92:93] offset:1024
	global_load_lds_dwordx4 v242, s[92:93] offset:2048
	global_load_lds_dwordx4 v243, s[92:93] offset:3072
	s_add_u32 s90, s90, 0x80
	s_addc_u32 s91, s91, 0
	s_add_u32 s92, s92, 0x80
	s_addc_u32 s93, s93, 0
	ds_read_b128 v[110:113], v244 offset:0
	ds_read_b128 v[114:117], v244 offset:2048
	ds_read_b128 v[118:121], v244 offset:4096
	ds_read_b128 v[122:125], v244 offset:6144
	ds_read_b128 v[126:129], v246 offset:0
	ds_read_b128 v[130:133], v246 offset:2048
	ds_read_b128 v[134:137], v246 offset:4096
	ds_read_b128 v[138:141], v246 offset:6144
	s_movk_i32 s95, 0x6
	s_cmp_eq_u32 s95, 0
	s_cbranch_scc1 .Lgemm_x465

; __device__ __forceinline__ void phase_merge(const bf16_t* G, const bf16_t* BO, const bf16_t* Wb, bf16_t* M, bf16_t* sm) {
;     ...
;     for (int t = blockIdx.x; t < 136 * 16; t += gridDim.x) {
;         const int tm = t >> 4, tn = t & 15;
;         const int cbase = tn * 64 + wc * 32 + fq * 8;
;         f32x4 accm[4][2]; zero_acc<2>(accm);
; #pragma unroll 1
;         for (int i = 0; i < 4; ++i) {
;             f32x4 accb[4][2]; zero_acc<2>(accb);
;             const int koff = i * 512, kk = i < 3 ? 512 : 256;
;             gemm_tile<2>(accb, BO + (size_t)tm * 128 * 1792 + koff, 1792, Wb + (size_t)tn * 64 * 1792 + koff, 1792, kk, sm);
.LBB0_474:
	s_bfe_u32 s2, s42, 0x30003
	s_and_b32 s24, s42, 1
	s_lshl_b32 s24, s24, 3
	s_or_b32 s2, s2, s24
	s_and_b32 s24, s42, 15
	s_cmpk_lt_i32 s42, 0x800
	s_cselect_b32 s2, s2, s24
	s_mov_b32 s40, s2
	s_mul_i32 s2, s2, 0x38000
	s_add_u32 s22, s58, s2
	s_addc_u32 s23, s59, 0
	s_lshr_b32 s2, s43, 9
	s_lshl_b32 s2, s2, 5
	s_bfe_u32 s24, s43, 0x20001
	s_lshl_b32 s24, s24, 3
	s_or_b32 s2, s2, s24
	s_bfe_u32 s24, s43, 0x30006
	s_or_b32 s2, s2, s24
	s_ashr_i32 s24, s43, 4
	s_cmpk_lt_i32 s43, 0x800
	s_cselect_b32 s2, s2, s24
	s_mov_b32 s24, s40
	s_mul_i32 s40, s2, 0x70000
	s_mul_hi_i32 s25, s2, 0x70000
	s_add_u32 s44, s11, s40
	v_lshl_or_b32 v66, s24, 6, v67
	s_addc_u32 s45, s12, s25
	s_mul_i32 s24, s24, 0x38000
	s_add_u32 s46, s13, s24
	v_lshl_add_u32 v64, s2, 7, v114
	s_addc_u32 s47, s39, 0
	v_or_b32_e32 v62, 16, v64
	v_or_b32_e32 v60, 32, v64
	v_or_b32_e32 v58, 48, v64
	v_lshlrev_b32_e32 v12, 1, v66
	v_ashrrev_i32_e32 v65, 31, v64
	v_ashrrev_i32_e32 v63, 31, v62
	v_ashrrev_i32_e32 v61, 31, v60
	v_ashrrev_i32_e32 v59, 31, v58
	s_add_u32 s24, s58, s40
	v_mov_b32_e32 v115, 0
	v_lshl_add_u64 v[76:77], s[14:15], 0, v[12:13]
	v_lshlrev_b64 v[78:79], 13, v[64:65]
	v_lshlrev_b64 v[80:81], 13, v[62:63]
	v_lshlrev_b64 v[90:91], 13, v[60:61]
	v_lshlrev_b64 v[92:93], 13, v[58:59]
	s_addc_u32 s25, s59, s25
	s_mov_b32 s48, 0
	v_mov_b32_e32 v75, 0
	v_mov_b32_e32 v73, 0
	v_mov_b32_e32 v71, 0
	v_mov_b32_e32 v69, 0
	v_mov_b32_e32 v74, v115
	v_mov_b32_e32 v72, v115
	v_mov_b32_e32 v70, v115
	v_mov_b32_e32 v68, v115
	v_mov_b32_e32 v89, 0
	v_mov_b32_e32 v87, 0
	v_mov_b32_e32 v85, 0
	v_mov_b32_e32 v83, 0
	v_mov_b32_e32 v88, v115
	v_mov_b32_e32 v86, v115
	v_mov_b32_e32 v84, v115
	v_mov_b32_e32 v82, v115
	v_mov_b32_e32 v101, 0
	v_mov_b32_e32 v99, 0
	v_mov_b32_e32 v97, 0
	v_mov_b32_e32 v95, 0
	v_mov_b32_e32 v100, v115
	v_mov_b32_e32 v98, v115
	v_mov_b32_e32 v96, v115
	v_mov_b32_e32 v94, v115
	v_mov_b32_e32 v109, 0
	v_mov_b32_e32 v107, 0
	v_mov_b32_e32 v105, 0
	v_mov_b32_e32 v103, 0
	v_mov_b32_e32 v108, v115
	v_mov_b32_e32 v106, v115
	v_mov_b32_e32 v104, v115
	v_mov_b32_e32 v102, v115
